# accumulator zeroing with v_mov_b64 pairs in 7 GEMM tile loops; GLU second-round tiles rotated to idle workgroups; ml_out sigmoid 1/x via v_rcp
# baseline (speedup 1.0000x reference)
.LBB0_239:
	s_ashr_i32 s31, s30, 31
	s_lshl_b64 s[34:35], s[30:31], 20
	v_readlane_b32 s5, v254, 25
	s_add_u32 s34, s5, s34
	v_readlane_b32 s5, v254, 26
	s_addc_u32 s35, s5, s35
	s_and_b64 s[36:37], s[2:3], exec
	s_cselect_b32 s5, s35, s39
	s_cselect_b32 s7, s34, s38
	s_ashr_i32 s29, s28, 31
	s_lshl_b64 s[36:37], s[28:29], 20
	s_add_u32 s36, s8, s36
	s_addc_u32 s37, s9, s37
	s_and_b64 s[42:43], s[2:3], exec
	s_cselect_b32 s29, s37, s41
	s_cselect_b32 s31, s36, s40
	s_add_u32 s38, s38, 0x80080
	s_addc_u32 s39, s39, 0
	s_add_u32 s51, s40, 0x100
	v_mov_b32_e32 v0, 0
	s_addc_u32 s52, s41, 0
	s_mov_b32 s53, -2
	v_mov_b32_e32 v1, v0
	v_mov_b64_e32 v[2:3], v[0:1]
	v_mov_b64_e32 v[4:5], v[0:1]
	v_mov_b64_e32 v[6:7], v[0:1]
	v_mov_b64_e32 v[8:9], v[0:1]
	v_mov_b64_e32 v[10:11], v[0:1]
	v_mov_b64_e32 v[12:13], v[0:1]
	v_mov_b64_e32 v[14:15], v[0:1]
	v_mov_b64_e32 v[16:17], v[0:1]
	v_mov_b64_e32 v[18:19], v[0:1]
	v_mov_b64_e32 v[20:21], v[0:1]
	v_mov_b64_e32 v[22:23], v[0:1]
	v_mov_b64_e32 v[24:25], v[0:1]
	v_mov_b64_e32 v[26:27], v[0:1]
	v_mov_b64_e32 v[28:29], v[0:1]
	v_mov_b64_e32 v[30:31], v[0:1]
	v_mov_b64_e32 v[32:33], v[0:1]
	v_mov_b64_e32 v[34:35], v[0:1]
	v_mov_b64_e32 v[36:37], v[0:1]
	v_mov_b64_e32 v[38:39], v[0:1]
	v_mov_b64_e32 v[40:41], v[0:1]
	v_mov_b64_e32 v[42:43], v[0:1]
	v_mov_b64_e32 v[44:45], v[0:1]
	v_mov_b64_e32 v[46:47], v[0:1]
	v_mov_b64_e32 v[48:49], v[0:1]
	v_mov_b64_e32 v[50:51], v[0:1]
	v_mov_b64_e32 v[52:53], v[0:1]
	v_mov_b64_e32 v[54:55], v[0:1]
	v_mov_b64_e32 v[56:57], v[0:1]
	v_mov_b64_e32 v[58:59], v[0:1]
	v_mov_b64_e32 v[60:61], v[0:1]
	v_mov_b64_e32 v[62:63], v[0:1]
	v_mov_b64_e32 v[72:73], v[0:1]
	v_mov_b64_e32 v[74:75], v[0:1]
	v_mov_b64_e32 v[76:77], v[0:1]
	v_mov_b64_e32 v[78:79], v[0:1]
	v_mov_b64_e32 v[88:89], v[0:1]
	v_mov_b64_e32 v[90:91], v[0:1]
	v_mov_b64_e32 v[92:93], v[0:1]
	v_mov_b64_e32 v[94:95], v[0:1]
	v_mov_b64_e32 v[96:97], v[0:1]
	v_mov_b64_e32 v[98:99], v[0:1]
	v_mov_b64_e32 v[100:101], v[0:1]
	v_mov_b64_e32 v[102:103], v[0:1]
	v_mov_b64_e32 v[104:105], v[0:1]
	v_mov_b64_e32 v[106:107], v[0:1]
	v_mov_b64_e32 v[108:109], v[0:1]
	v_mov_b64_e32 v[110:111], v[0:1]
	v_mov_b64_e32 v[112:113], v[0:1]
	v_mov_b64_e32 v[114:115], v[0:1]
	v_mov_b64_e32 v[116:117], v[0:1]
	v_mov_b64_e32 v[118:119], v[0:1]
	v_mov_b64_e32 v[120:121], v[0:1]
	v_mov_b64_e32 v[122:123], v[0:1]
	v_mov_b64_e32 v[124:125], v[0:1]
	v_mov_b64_e32 v[126:127], v[0:1]
	v_mov_b64_e32 v[128:129], v[0:1]
	v_mov_b64_e32 v[130:131], v[0:1]
	v_mov_b64_e32 v[132:133], v[0:1]
	v_mov_b64_e32 v[134:135], v[0:1]
	v_mov_b64_e32 v[136:137], v[0:1]
	v_mov_b64_e32 v[138:139], v[0:1]
	v_mov_b64_e32 v[140:141], v[0:1]
	v_mov_b64_e32 v[142:143], v[0:1]

.LBB0_351:
	s_ashr_i32 s15, s14, 31
	s_lshl_b64 s[16:17], s[14:15], 20
	s_add_u32 s16, s24, s16
	s_addc_u32 s17, s36, s17
	s_and_b64 s[18:19], s[2:3], exec
	s_cselect_b32 s15, s17, s29
	s_cselect_b32 s47, s16, s28
	s_ashr_i32 s13, s12, 31
	s_lshl_b64 s[18:19], s[12:13], 20
	v_readlane_b32 s13, v254, 25
	s_add_u32 s18, s13, s18
	v_readlane_b32 s13, v254, 26
	s_addc_u32 s19, s13, s19
	s_and_b64 s[34:35], s[2:3], exec
	s_cselect_b32 s13, s19, s31
	s_cselect_b32 s48, s18, s30
	s_add_u32 s28, s28, 0x80080
	s_addc_u32 s29, s29, 0
	s_add_u32 s49, s30, 0x100
	v_mov_b32_e32 v0, 0
	s_addc_u32 s50, s31, 0
	s_mov_b32 s51, -2
	v_mov_b32_e32 v1, v0
	v_mov_b64_e32 v[2:3], v[0:1]
	v_mov_b64_e32 v[4:5], v[0:1]
	v_mov_b64_e32 v[6:7], v[0:1]
	v_mov_b64_e32 v[8:9], v[0:1]
	v_mov_b64_e32 v[10:11], v[0:1]
	v_mov_b64_e32 v[12:13], v[0:1]
	v_mov_b64_e32 v[14:15], v[0:1]
	v_mov_b64_e32 v[16:17], v[0:1]
	v_mov_b64_e32 v[18:19], v[0:1]
	v_mov_b64_e32 v[20:21], v[0:1]
	v_mov_b64_e32 v[22:23], v[0:1]
	v_mov_b64_e32 v[24:25], v[0:1]
	v_mov_b64_e32 v[26:27], v[0:1]
	v_mov_b64_e32 v[28:29], v[0:1]
	v_mov_b64_e32 v[30:31], v[0:1]
	v_mov_b64_e32 v[32:33], v[0:1]
	v_mov_b64_e32 v[34:35], v[0:1]
	v_mov_b64_e32 v[36:37], v[0:1]
	v_mov_b64_e32 v[38:39], v[0:1]
	v_mov_b64_e32 v[40:41], v[0:1]
	v_mov_b64_e32 v[42:43], v[0:1]
	v_mov_b64_e32 v[44:45], v[0:1]
	v_mov_b64_e32 v[46:47], v[0:1]
	v_mov_b64_e32 v[48:49], v[0:1]
	v_mov_b64_e32 v[50:51], v[0:1]
	v_mov_b64_e32 v[52:53], v[0:1]
	v_mov_b64_e32 v[54:55], v[0:1]
	v_mov_b64_e32 v[56:57], v[0:1]
	v_mov_b64_e32 v[58:59], v[0:1]
	v_mov_b64_e32 v[60:61], v[0:1]
	v_mov_b64_e32 v[62:63], v[0:1]
	v_mov_b64_e32 v[64:65], v[0:1]
	v_mov_b64_e32 v[66:67], v[0:1]
	v_mov_b64_e32 v[68:69], v[0:1]
	v_mov_b64_e32 v[70:71], v[0:1]
	v_mov_b64_e32 v[72:73], v[0:1]
	v_mov_b64_e32 v[74:75], v[0:1]
	v_mov_b64_e32 v[76:77], v[0:1]
	v_mov_b64_e32 v[78:79], v[0:1]
	v_mov_b64_e32 v[80:81], v[0:1]
	v_mov_b64_e32 v[82:83], v[0:1]
	v_mov_b64_e32 v[84:85], v[0:1]
	v_mov_b64_e32 v[86:87], v[0:1]
	v_mov_b64_e32 v[88:89], v[0:1]
	v_mov_b64_e32 v[90:91], v[0:1]
	v_mov_b64_e32 v[92:93], v[0:1]
	v_mov_b64_e32 v[94:95], v[0:1]
	v_mov_b64_e32 v[96:97], v[0:1]
	v_mov_b64_e32 v[98:99], v[0:1]
	v_mov_b64_e32 v[100:101], v[0:1]
	v_mov_b64_e32 v[102:103], v[0:1]
	v_mov_b64_e32 v[104:105], v[0:1]
	v_mov_b64_e32 v[106:107], v[0:1]
	v_mov_b64_e32 v[108:109], v[0:1]
	v_mov_b64_e32 v[110:111], v[0:1]
	v_mov_b64_e32 v[112:113], v[0:1]
	v_mov_b64_e32 v[114:115], v[0:1]
	v_mov_b64_e32 v[116:117], v[0:1]
	v_mov_b64_e32 v[118:119], v[0:1]
	v_mov_b64_e32 v[120:121], v[0:1]
	v_mov_b64_e32 v[122:123], v[0:1]
	v_mov_b64_e32 v[124:125], v[0:1]
	v_mov_b64_e32 v[126:127], v[0:1]

.LBB0_525:
	s_ashr_i32 s13, s12, 31
	s_lshl_b64 s[14:15], s[12:13], 21
	s_add_u32 s14, s24, s14
	s_addc_u32 s15, s34, s15
	s_and_b64 s[16:17], s[2:3], exec
	s_cselect_b32 s13, s15, s19
	s_cselect_b32 s49, s14, s18
	s_ashr_i32 s11, s10, 31
	s_lshl_b64 s[16:17], s[10:11], 18
	s_add_u32 s16, s35, s16
	s_addc_u32 s17, s36, s17
	s_and_b64 s[30:31], s[2:3], exec
	s_cselect_b32 s11, s17, s29
	s_cselect_b32 s50, s16, s28
	s_add_u32 s18, s18, 0x100080
	s_addc_u32 s19, s19, 0
	s_add_u32 s51, s28, 0x100
	v_mov_b32_e32 v0, 0
	s_addc_u32 s52, s29, 0
	s_mov_b32 s53, -2
	v_mov_b32_e32 v1, v0
	v_mov_b64_e32 v[2:3], v[0:1]
	v_mov_b64_e32 v[4:5], v[0:1]
	v_mov_b64_e32 v[6:7], v[0:1]
	v_mov_b64_e32 v[8:9], v[0:1]
	v_mov_b64_e32 v[10:11], v[0:1]
	v_mov_b64_e32 v[12:13], v[0:1]
	v_mov_b64_e32 v[14:15], v[0:1]
	v_mov_b64_e32 v[16:17], v[0:1]
	v_mov_b64_e32 v[18:19], v[0:1]
	v_mov_b64_e32 v[20:21], v[0:1]
	v_mov_b64_e32 v[22:23], v[0:1]
	v_mov_b64_e32 v[24:25], v[0:1]
	v_mov_b64_e32 v[26:27], v[0:1]
	v_mov_b64_e32 v[28:29], v[0:1]
	v_mov_b64_e32 v[30:31], v[0:1]
	v_mov_b64_e32 v[32:33], v[0:1]
	v_mov_b64_e32 v[34:35], v[0:1]
	v_mov_b64_e32 v[36:37], v[0:1]
	v_mov_b64_e32 v[38:39], v[0:1]
	v_mov_b64_e32 v[40:41], v[0:1]
	v_mov_b64_e32 v[42:43], v[0:1]
	v_mov_b64_e32 v[44:45], v[0:1]
	v_mov_b64_e32 v[46:47], v[0:1]
	v_mov_b64_e32 v[48:49], v[0:1]
	v_mov_b64_e32 v[50:51], v[0:1]
	v_mov_b64_e32 v[52:53], v[0:1]
	v_mov_b64_e32 v[54:55], v[0:1]
	v_mov_b64_e32 v[56:57], v[0:1]
	v_mov_b64_e32 v[58:59], v[0:1]
	v_mov_b64_e32 v[60:61], v[0:1]
	v_mov_b64_e32 v[62:63], v[0:1]
	v_mov_b64_e32 v[64:65], v[0:1]
	v_mov_b64_e32 v[66:67], v[0:1]
	v_mov_b64_e32 v[68:69], v[0:1]
	v_mov_b64_e32 v[70:71], v[0:1]
	v_mov_b64_e32 v[72:73], v[0:1]
	v_mov_b64_e32 v[74:75], v[0:1]
	v_mov_b64_e32 v[76:77], v[0:1]
	v_mov_b64_e32 v[78:79], v[0:1]
	v_mov_b64_e32 v[80:81], v[0:1]
	v_mov_b64_e32 v[82:83], v[0:1]
	v_mov_b64_e32 v[84:85], v[0:1]
	v_mov_b64_e32 v[86:87], v[0:1]
	v_mov_b64_e32 v[88:89], v[0:1]
	v_mov_b64_e32 v[90:91], v[0:1]
	v_mov_b64_e32 v[92:93], v[0:1]
	v_mov_b64_e32 v[94:95], v[0:1]
	v_mov_b64_e32 v[96:97], v[0:1]
	v_mov_b64_e32 v[98:99], v[0:1]
	v_mov_b64_e32 v[100:101], v[0:1]
	v_mov_b64_e32 v[102:103], v[0:1]
	v_mov_b64_e32 v[104:105], v[0:1]
	v_mov_b64_e32 v[106:107], v[0:1]
	v_mov_b64_e32 v[108:109], v[0:1]
	v_mov_b64_e32 v[110:111], v[0:1]
	v_mov_b64_e32 v[112:113], v[0:1]
	v_mov_b64_e32 v[114:115], v[0:1]
	v_mov_b64_e32 v[116:117], v[0:1]
	v_mov_b64_e32 v[118:119], v[0:1]
	v_mov_b64_e32 v[120:121], v[0:1]
	v_mov_b64_e32 v[122:123], v[0:1]
	v_mov_b64_e32 v[124:125], v[0:1]
	v_mov_b64_e32 v[126:127], v[0:1]

.LBB0_541:
	s_ashr_i32 s15, s14, 31
	s_lshl_b64 s[16:17], s[14:15], 21
	s_add_u32 s16, s24, s16
	s_addc_u32 s17, s34, s17
	s_and_b64 s[18:19], s[4:5], exec
	s_cselect_b32 s15, s17, s27
	s_cselect_b32 s49, s16, s26
	s_ashr_i32 s13, s12, 31
	s_lshl_b64 s[18:19], s[12:13], 18
	s_add_u32 s18, s35, s18
	s_addc_u32 s19, s36, s19
	s_and_b64 s[30:31], s[4:5], exec
	s_cselect_b32 s13, s19, s29
	s_cselect_b32 s50, s18, s28
	s_add_u32 s26, s26, 0x100080
	s_addc_u32 s27, s27, 0
	s_add_u32 s51, s28, 0x100
	v_mov_b32_e32 v0, 0
	s_addc_u32 s52, s29, 0
	s_mov_b32 s53, -2
	v_mov_b32_e32 v1, v0
	v_mov_b64_e32 v[2:3], v[0:1]
	v_mov_b64_e32 v[4:5], v[0:1]
	v_mov_b64_e32 v[6:7], v[0:1]
	v_mov_b64_e32 v[8:9], v[0:1]
	v_mov_b64_e32 v[10:11], v[0:1]
	v_mov_b64_e32 v[12:13], v[0:1]
	v_mov_b64_e32 v[14:15], v[0:1]
	v_mov_b64_e32 v[16:17], v[0:1]
	v_mov_b64_e32 v[18:19], v[0:1]
	v_mov_b64_e32 v[20:21], v[0:1]
	v_mov_b64_e32 v[22:23], v[0:1]
	v_mov_b64_e32 v[24:25], v[0:1]
	v_mov_b64_e32 v[26:27], v[0:1]
	v_mov_b64_e32 v[28:29], v[0:1]
	v_mov_b64_e32 v[30:31], v[0:1]
	v_mov_b64_e32 v[32:33], v[0:1]
	v_mov_b64_e32 v[34:35], v[0:1]
	v_mov_b64_e32 v[36:37], v[0:1]
	v_mov_b64_e32 v[38:39], v[0:1]
	v_mov_b64_e32 v[40:41], v[0:1]
	v_mov_b64_e32 v[42:43], v[0:1]
	v_mov_b64_e32 v[44:45], v[0:1]
	v_mov_b64_e32 v[46:47], v[0:1]
	v_mov_b64_e32 v[48:49], v[0:1]
	v_mov_b64_e32 v[50:51], v[0:1]
	v_mov_b64_e32 v[52:53], v[0:1]
	v_mov_b64_e32 v[54:55], v[0:1]
	v_mov_b64_e32 v[56:57], v[0:1]
	v_mov_b64_e32 v[58:59], v[0:1]
	v_mov_b64_e32 v[60:61], v[0:1]
	v_mov_b64_e32 v[62:63], v[0:1]
	v_mov_b64_e32 v[64:65], v[0:1]
	v_mov_b64_e32 v[66:67], v[0:1]
	v_mov_b64_e32 v[68:69], v[0:1]
	v_mov_b64_e32 v[70:71], v[0:1]
	v_mov_b64_e32 v[72:73], v[0:1]
	v_mov_b64_e32 v[74:75], v[0:1]
	v_mov_b64_e32 v[76:77], v[0:1]
	v_mov_b64_e32 v[78:79], v[0:1]
	v_mov_b64_e32 v[80:81], v[0:1]
	v_mov_b64_e32 v[82:83], v[0:1]
	v_mov_b64_e32 v[84:85], v[0:1]
	v_mov_b64_e32 v[86:87], v[0:1]
	v_mov_b64_e32 v[88:89], v[0:1]
	v_mov_b64_e32 v[90:91], v[0:1]
	v_mov_b64_e32 v[92:93], v[0:1]
	v_mov_b64_e32 v[94:95], v[0:1]
	v_mov_b64_e32 v[96:97], v[0:1]
	v_mov_b64_e32 v[98:99], v[0:1]
	v_mov_b64_e32 v[100:101], v[0:1]
	v_mov_b64_e32 v[102:103], v[0:1]
	v_mov_b64_e32 v[104:105], v[0:1]
	v_mov_b64_e32 v[106:107], v[0:1]
	v_mov_b64_e32 v[108:109], v[0:1]
	v_mov_b64_e32 v[110:111], v[0:1]
	v_mov_b64_e32 v[112:113], v[0:1]
	v_mov_b64_e32 v[114:115], v[0:1]
	v_mov_b64_e32 v[116:117], v[0:1]
	v_mov_b64_e32 v[118:119], v[0:1]
	v_mov_b64_e32 v[120:121], v[0:1]
	v_mov_b64_e32 v[122:123], v[0:1]
	v_mov_b64_e32 v[124:125], v[0:1]
	v_mov_b64_e32 v[126:127], v[0:1]

.LBB0_557:
	s_ashr_i32 s13, s12, 31
	s_lshl_b64 s[14:15], s[12:13], 18
	s_add_u32 s14, s30, s14
	s_addc_u32 s15, s31, s15
	s_and_b64 s[16:17], s[2:3], exec
	s_cselect_b32 s13, s15, s19
	s_cselect_b32 s47, s14, s18
	s_ashr_i32 s11, s10, 31
	s_lshl_b64 s[16:17], s[10:11], 21
	s_add_u32 s16, s24, s16
	s_addc_u32 s17, s34, s17
	s_and_b64 s[28:29], s[2:3], exec
	s_cselect_b32 s11, s17, s27
	s_cselect_b32 s48, s16, s26
	s_add_u32 s18, s18, 0x20080
	s_addc_u32 s19, s19, 0
	s_add_u32 s49, s26, 0x100
	v_mov_b32_e32 v0, 0
	s_addc_u32 s50, s27, 0
	s_mov_b32 s51, -2
	v_mov_b32_e32 v1, v0
	v_mov_b64_e32 v[2:3], v[0:1]
	v_mov_b64_e32 v[4:5], v[0:1]
	v_mov_b64_e32 v[6:7], v[0:1]
	v_mov_b64_e32 v[8:9], v[0:1]
	v_mov_b64_e32 v[10:11], v[0:1]
	v_mov_b64_e32 v[12:13], v[0:1]
	v_mov_b64_e32 v[14:15], v[0:1]
	v_mov_b64_e32 v[16:17], v[0:1]
	v_mov_b64_e32 v[18:19], v[0:1]
	v_mov_b64_e32 v[20:21], v[0:1]
	v_mov_b64_e32 v[22:23], v[0:1]
	v_mov_b64_e32 v[24:25], v[0:1]
	v_mov_b64_e32 v[26:27], v[0:1]
	v_mov_b64_e32 v[28:29], v[0:1]
	v_mov_b64_e32 v[30:31], v[0:1]
	v_mov_b64_e32 v[32:33], v[0:1]
	v_mov_b64_e32 v[34:35], v[0:1]
	v_mov_b64_e32 v[36:37], v[0:1]
	v_mov_b64_e32 v[38:39], v[0:1]
	v_mov_b64_e32 v[40:41], v[0:1]
	v_mov_b64_e32 v[42:43], v[0:1]
	v_mov_b64_e32 v[44:45], v[0:1]
	v_mov_b64_e32 v[46:47], v[0:1]
	v_mov_b64_e32 v[48:49], v[0:1]
	v_mov_b64_e32 v[50:51], v[0:1]
	v_mov_b64_e32 v[52:53], v[0:1]
	v_mov_b64_e32 v[54:55], v[0:1]
	v_mov_b64_e32 v[56:57], v[0:1]
	v_mov_b64_e32 v[58:59], v[0:1]
	v_mov_b64_e32 v[60:61], v[0:1]
	v_mov_b64_e32 v[62:63], v[0:1]
	v_mov_b64_e32 v[64:65], v[0:1]
	v_mov_b64_e32 v[66:67], v[0:1]
	v_mov_b64_e32 v[68:69], v[0:1]
	v_mov_b64_e32 v[70:71], v[0:1]
	v_mov_b64_e32 v[72:73], v[0:1]
	v_mov_b64_e32 v[74:75], v[0:1]
	v_mov_b64_e32 v[76:77], v[0:1]
	v_mov_b64_e32 v[78:79], v[0:1]
	v_mov_b64_e32 v[80:81], v[0:1]
	v_mov_b64_e32 v[82:83], v[0:1]
	v_mov_b64_e32 v[84:85], v[0:1]
	v_mov_b64_e32 v[86:87], v[0:1]
	v_mov_b64_e32 v[88:89], v[0:1]
	v_mov_b64_e32 v[90:91], v[0:1]
	v_mov_b64_e32 v[92:93], v[0:1]
	v_mov_b64_e32 v[94:95], v[0:1]
	v_mov_b64_e32 v[96:97], v[0:1]
	v_mov_b64_e32 v[98:99], v[0:1]
	v_mov_b64_e32 v[100:101], v[0:1]
	v_mov_b64_e32 v[102:103], v[0:1]
	v_mov_b64_e32 v[104:105], v[0:1]
	v_mov_b64_e32 v[106:107], v[0:1]
	v_mov_b64_e32 v[108:109], v[0:1]
	v_mov_b64_e32 v[110:111], v[0:1]
	v_mov_b64_e32 v[112:113], v[0:1]
	v_mov_b64_e32 v[114:115], v[0:1]
	v_mov_b64_e32 v[116:117], v[0:1]
	v_mov_b64_e32 v[118:119], v[0:1]
	v_mov_b64_e32 v[120:121], v[0:1]
	v_mov_b64_e32 v[122:123], v[0:1]
	v_mov_b64_e32 v[124:125], v[0:1]
	v_mov_b64_e32 v[126:127], v[0:1]

.LBB0_879:
	v_sub_f32_e32 v115, v142, v150
	v_mul_f32_e32 v115, 0x3fb8aa3b, v115
	v_exp_f32_e32 v115, v115
	v_add_f32_e32 v117, v148, v149
	v_add_f32_e32 v119, v151, v152
	s_lshl_b32 s24, s72, 9
	v_mul_f32_e32 v117, v115, v117
	v_fmac_f32_e32 v119, 0x3db504f3, v117
	v_add_f32_e32 v117, v140, v150
	v_mul_f32_e32 v117, 0xbfb8aa3b, v117
	v_exp_f32_e32 v117, v117
	v_mul_f32_e32 v142, 0x3db504f3, v115
	v_sub_f32_e32 v115, v141, v145
	v_mul_f32_e32 v115, 0x3fb8aa3b, v115
	v_max_f32_e64 v117, |v119|, v117
	v_exp_f32_e32 v115, v115
	v_lshl_add_u64 v[132:133], v[156:157], 0, s[24:25]
	v_mov_b32_e32 v152, v142
	v_rcp_f32_e32 v140, v117
	v_add_f32_e32 v117, v143, v144
	v_add_f32_e32 v119, v146, v147
	v_mul_f32_e32 v117, v115, v117
	v_fmac_f32_e32 v119, 0x3db504f3, v117
	v_add_f32_e32 v117, v131, v145
	v_mul_f32_e32 v117, 0xbfb8aa3b, v117
	v_exp_f32_e32 v117, v117
	v_mul_f32_e32 v146, 0x3db504f3, v115
	v_mov_b32_e32 v147, v146
	v_mov_b32_e32 v148, v146
	v_max_f32_e64 v117, |v119|, v117
	v_mov_b32_e32 v149, v146
	v_mov_b32_e32 v143, v142
	v_mov_b32_e32 v153, v142
	v_rcp_f32_e32 v144, v117
	s_nop 0
	v_mov_b32_e32 v145, v144
	v_mov_b32_e32 v150, v144
	v_mov_b32_e32 v151, v144
	v_mov_b32_e32 v141, v140
	v_mov_b32_e32 v154, v140
	v_mov_b32_e32 v155, v140
	s_mov_b32 s73, s25
	v_lshl_add_u64 v[156:157], v[106:107], 0, v[132:133]
	s_mov_b32 s19, 0
	v_mov_b32_e32 v117, 0
	v_add_u32_e32 v115, 0x2000, v96
	v_add_u32_e32 v119, 0x2000, v92
	v_add_u32_e32 v121, 0x2000, v88
	v_add_u32_e32 v123, 0x2000, v84
	v_add_u32_e32 v125, 0x2000, v100
	v_add_u32_e32 v127, 0x2000, v104

.LBB0_923:
	global_load_dwordx4 v[32:35], v[12:13], off offset:-192
	global_load_dwordx4 v[8:11], v[12:13], off offset:-128
	global_load_dwordx2 v[36:37], v[14:15], off offset:-64
	global_load_dwordx2 v[26:27], v[14:15], off offset:-32
	global_load_dwordx2 v[22:23], v[14:15], off
	global_load_dwordx2 v[18:19], v[14:15], off offset:32
	global_load_dwordx4 v[4:7], v[12:13], off offset:-64
	global_load_dwordx4 v[0:3], v[12:13], off
	global_load_dwordx2 v[38:39], v[16:17], off offset:-64
	global_load_dwordx2 v[28:29], v[16:17], off offset:-32
	global_load_dwordx2 v[24:25], v[16:17], off
	global_load_dwordx2 v[20:21], v[16:17], off offset:32
	s_waitcnt vmcnt(9)
	v_lshlrev_b32_e32 v31, 16, v36
	v_mul_f32_e32 v31, 0xbfb8aa3b, v31
	v_exp_f32_e32 v31, v31
	s_waitcnt vmcnt(3)
	v_lshlrev_b32_e32 v41, 16, v38
	v_mul_f32_e32 v41, v30, v41
	v_mul_f32_e32 v32, v32, v41
	v_add_f32_e32 v31, 1.0, v31
	v_and_b32_e32 v38, 0xffff0000, v38
	v_and_b32_e32 v36, 0xffff0000, v36
	v_lshlrev_b32_e32 v40, 16, v37
	v_rcp_f32_e32 v31, v31
	s_nop 0
	v_mul_f32_e32 v31, v32, v31
	v_mul_f32_e32 v32, v30, v38
	v_mul_f32_e32 v32, v33, v32
	v_mul_f32_e32 v33, 0xbfb8aa3b, v36
	v_exp_f32_e32 v33, v33
	v_lshlrev_b32_e32 v42, 16, v39
	v_and_b32_e32 v37, 0xffff0000, v37
	v_and_b32_e32 v39, 0xffff0000, v39
	v_add_f32_e32 v33, 1.0, v33
	s_add_i32 s4, s4, 4
	v_lshl_add_u64 v[14:15], v[14:15], 0, s[20:21]
	s_cmp_lt_u32 s4, 12
	v_rcp_f32_e32 v33, v33
	s_nop 0
	v_mul_f32_e32 v32, v32, v33
	v_mul_f32_e32 v33, 0xbfb8aa3b, v40
	v_exp_f32_e32 v33, v33
	v_cvt_pk_bf16_f32 v32, v31, v32
	v_mul_f32_e32 v31, v30, v42
	v_mul_f32_e32 v31, v34, v31
	v_add_f32_e32 v33, 1.0, v33
	s_nop 0
	v_rcp_f32_e32 v33, v33
	v_mul_f32_e32 v34, 0xbfb8aa3b, v37
	v_exp_f32_e32 v34, v34
	v_mul_f32_e32 v31, v31, v33
	v_mul_f32_e32 v33, v30, v39
	v_mul_f32_e32 v33, v35, v33
	v_add_f32_e32 v34, 1.0, v34
	s_nop 0
	v_rcp_f32_e32 v34, v34
	s_nop 0
	v_mul_f32_e32 v33, v33, v34
	v_cvt_pk_bf16_f32 v33, v31, v33
	v_lshlrev_b32_e32 v31, 16, v26
	v_mul_f32_e32 v31, 0xbfb8aa3b, v31
	v_exp_f32_e32 v31, v31
	global_store_dwordx2 v[16:17], v[32:33], off offset:-64
	s_waitcnt vmcnt(3)
	v_lshlrev_b32_e32 v33, 16, v28
	v_mul_f32_e32 v33, v30, v33
	v_add_f32_e32 v31, 1.0, v31
	v_mul_f32_e32 v8, v8, v33
	v_and_b32_e32 v26, 0xffff0000, v26
	v_mul_f32_e32 v26, 0xbfb8aa3b, v26
	v_exp_f32_e32 v26, v26
	v_and_b32_e32 v28, 0xffff0000, v28
	v_mul_f32_e32 v28, v30, v28
	v_add_f32_e32 v26, 1.0, v26
	v_rcp_f32_e32 v31, v31
	v_mul_f32_e32 v9, v9, v28
	v_mul_f32_e32 v8, v8, v31
	v_lshlrev_b32_e32 v34, 16, v29
	v_lshlrev_b32_e32 v32, 16, v27
	v_and_b32_e32 v29, 0xffff0000, v29
	v_rcp_f32_e32 v26, v26
	s_nop 0
	v_mul_f32_e32 v9, v9, v26
	v_cvt_pk_bf16_f32 v8, v8, v9
	v_mul_f32_e32 v9, v30, v34
	v_mul_f32_e32 v9, v10, v9
	v_mul_f32_e32 v10, 0xbfb8aa3b, v32
	v_exp_f32_e32 v10, v10
	v_and_b32_e32 v27, 0xffff0000, v27
	v_add_f32_e32 v10, 1.0, v10
	s_nop 0
	v_rcp_f32_e32 v10, v10
	s_nop 0
	v_mul_f32_e32 v9, v9, v10
	v_mul_f32_e32 v10, v30, v29
	v_mul_f32_e32 v10, v11, v10
	v_mul_f32_e32 v11, 0xbfb8aa3b, v27
	v_exp_f32_e32 v11, v11
	s_nop 0
	v_add_f32_e32 v11, 1.0, v11
	s_nop 0
	v_rcp_f32_e32 v11, v11
	s_nop 0
	v_mul_f32_e32 v10, v10, v11
	v_cvt_pk_bf16_f32 v9, v9, v10
	global_store_dwordx2 v[16:17], v[8:9], off offset:-32
	v_lshlrev_b32_e32 v8, 16, v22
	v_mul_f32_e32 v8, 0xbfb8aa3b, v8
	v_exp_f32_e32 v8, v8
	v_and_b32_e32 v9, 0xffff0000, v22
	s_waitcnt vmcnt(3)
	v_lshlrev_b32_e32 v22, 16, v24
	v_mul_f32_e32 v22, v30, v22
	v_add_f32_e32 v8, 1.0, v8
	v_mul_f32_e32 v4, v4, v22
	v_lshlrev_b32_e32 v10, 16, v23
	v_and_b32_e32 v11, 0xffff0000, v23
	v_and_b32_e32 v23, 0xffff0000, v24
	v_rcp_f32_e32 v8, v8
	s_nop 0
	v_mul_f32_e32 v4, v4, v8
	v_mul_f32_e32 v8, v30, v23
	v_mul_f32_e32 v5, v5, v8
	v_mul_f32_e32 v8, 0xbfb8aa3b, v9
	v_exp_f32_e32 v8, v8
	v_lshlrev_b32_e32 v24, 16, v25
	v_and_b32_e32 v25, 0xffff0000, v25
	v_add_f32_e32 v8, 1.0, v8
	s_nop 0
	v_rcp_f32_e32 v8, v8
	s_nop 0
	v_mul_f32_e32 v5, v5, v8
	v_cvt_pk_bf16_f32 v4, v4, v5
	v_mul_f32_e32 v5, v30, v24
	v_mul_f32_e32 v5, v6, v5
	v_mul_f32_e32 v6, 0xbfb8aa3b, v10
	v_exp_f32_e32 v6, v6
	s_nop 0
	v_add_f32_e32 v6, 1.0, v6
	s_nop 0
	v_rcp_f32_e32 v6, v6
	s_nop 0
	v_mul_f32_e32 v5, v5, v6
	v_mul_f32_e32 v6, v30, v25
	v_mul_f32_e32 v6, v7, v6
	v_mul_f32_e32 v7, 0xbfb8aa3b, v11
	v_exp_f32_e32 v7, v7
	s_nop 0
	v_add_f32_e32 v7, 1.0, v7
	s_nop 0
	v_rcp_f32_e32 v7, v7
	s_nop 0
	v_mul_f32_e32 v6, v6, v7
	v_cvt_pk_bf16_f32 v5, v5, v6
	global_store_dwordx2 v[16:17], v[4:5], off
	v_lshlrev_b32_e32 v4, 16, v18
	v_mul_f32_e32 v4, 0xbfb8aa3b, v4
	v_exp_f32_e32 v4, v4
	s_waitcnt vmcnt(3)
	v_lshlrev_b32_e32 v8, 16, v20
	v_mul_f32_e32 v8, v30, v8
	v_mul_f32_e32 v0, v0, v8
	v_add_f32_e32 v4, 1.0, v4
	v_and_b32_e32 v5, 0xffff0000, v18
	v_lshlrev_b32_e32 v6, 16, v19
	v_and_b32_e32 v7, 0xffff0000, v19
	v_and_b32_e32 v9, 0xffff0000, v20
	v_lshlrev_b32_e32 v10, 16, v21
	v_and_b32_e32 v11, 0xffff0000, v21
	v_rcp_f32_e32 v4, v4
	s_nop 0
	v_mul_f32_e32 v0, v0, v4
	v_mul_f32_e32 v4, v30, v9
	v_mul_f32_e32 v1, v1, v4
	v_mul_f32_e32 v4, 0xbfb8aa3b, v5
	v_exp_f32_e32 v4, v4
	s_nop 0
	v_add_f32_e32 v4, 1.0, v4
	s_nop 0
	v_rcp_f32_e32 v4, v4
	s_nop 0
	v_mul_f32_e32 v1, v1, v4
	v_cvt_pk_bf16_f32 v0, v0, v1
	v_mul_f32_e32 v1, v30, v10
	v_mul_f32_e32 v1, v2, v1
	v_mul_f32_e32 v2, 0xbfb8aa3b, v6
	v_exp_f32_e32 v2, v2
	s_nop 0
	v_add_f32_e32 v2, 1.0, v2
	s_nop 0
	v_rcp_f32_e32 v2, v2
	s_nop 0
	v_mul_f32_e32 v1, v1, v2
	v_mul_f32_e32 v2, v30, v11
	v_mul_f32_e32 v2, v3, v2
	v_mul_f32_e32 v3, 0xbfb8aa3b, v7
	v_exp_f32_e32 v3, v3
	s_nop 0
	v_add_f32_e32 v3, 1.0, v3
	s_mov_b64 s[10:11], 0x100
	v_lshl_add_u64 v[12:13], v[12:13], 0, s[10:11]
	v_rcp_f32_e32 v3, v3
	s_nop 0
	v_mul_f32_e32 v2, v2, v3
	v_cvt_pk_bf16_f32 v1, v1, v2
	global_store_dwordx2 v[16:17], v[0:1], off offset:32
	v_lshl_add_u64 v[16:17], v[16:17], 0, s[20:21]
	s_cbranch_scc1 .LBB0_923
	s_branch .LBB0_786

.LBB0_1021:
	s_add_i32 s53, s53, 1
	v_readlane_b32 s13, v252, 63
	s_mul_i32 s13, s53, s13
	s_mul_hi_u32 s15, s53, s33
	s_add_i32 s15, s15, s13
	s_mul_i32 s13, s53, s33
	v_readlane_b32 s16, v253, 14
	s_add_u32 s16, s13, s16
	v_readlane_b32 s13, v252, 62
	s_addc_u32 s17, s15, s13
	s_cmp_eq_u32 s33, 0x100
	s_cbranch_scc0 .Lrot_glu_done
	v_readlane_b32 s13, v253, 14
	s_nop 0
	s_cmp_lt_u32 s13, 240
	s_cselect_b32 s13, 0x100000, 0
	s_add_u32 s16, s16, s13
	s_addc_u32 s17, s17, 0
	s_sub_u32 s16, s16, 240
	s_subb_u32 s17, s17, 0
.Lrot_glu_done:
	v_mov_b64_e32 v[0:1], s[24:25]
	v_cmp_ge_i64_e32 vcc, s[16:17], v[0:1]
	v_cmp_lt_i64_e64 s[38:39], s[16:17], v[0:1]
	s_cbranch_vccnz .LBB0_1023
	s_ashr_i32 s12, s16, 31
	s_lshr_b32 s12, s12, 29
	s_add_i32 s12, s16, s12
	s_ashr_i32 s13, s12, 3
	s_and_b32 s12, s12, -8
	s_sub_i32 s12, s16, s12
	s_cmp_lt_i32 s12, 0
	s_cselect_b32 s14, s46, s45
	s_mul_i32 s12, s14, s12
	s_add_i32 s12, s12, s13
	s_ashr_i32 s13, s12, 31
	s_lshr_b32 s13, s13, 27
	s_add_i32 s13, s12, s13
	s_ashr_i32 s14, s13, 5
	s_lshl_b32 s14, s14, 3
	s_sub_i32 s15, s43, s14
	s_min_i32 s15, s15, 8
	s_abs_i32 s16, s15
	v_cvt_f32_u32_e32 v0, s16
	s_sub_i32 s18, 0, s16
	s_andn2_b32 s13, s13, 31
	s_sub_i32 s13, s12, s13
	v_rcp_iflag_f32_e32 v0, v0
	s_abs_i32 s12, s13
	s_xor_b32 s17, s13, s15
	s_ashr_i32 s17, s17, 31
	v_mul_f32_e32 v0, 0x4f7ffffe, v0
	v_cvt_u32_f32_e32 v0, v0
	s_nop 0
	v_readfirstlane_b32 s19, v0
	s_mul_i32 s18, s18, s19
	s_mul_hi_u32 s18, s19, s18
	s_add_i32 s19, s19, s18
	s_mul_hi_u32 s18, s12, s19
	s_mul_i32 s19, s18, s16
	s_sub_i32 s12, s12, s19
	s_add_i32 s34, s18, 1
	s_sub_i32 s19, s12, s16
	s_cmp_ge_u32 s12, s16
	s_cselect_b32 s18, s34, s18
	s_cselect_b32 s12, s19, s12
	s_add_i32 s19, s18, 1
	s_cmp_ge_u32 s12, s16
	s_cselect_b32 s12, s19, s18
	s_xor_b32 s12, s12, s17
	s_sub_i32 s12, s12, s17
	s_mul_i32 s15, s12, s15
	s_sub_i32 s13, s13, s15
	s_add_i32 s14, s13, s14

.LBB0_1450:
	s_ashr_i32 s15, s14, 31
	s_lshl_b64 s[16:17], s[14:15], 20
	v_readlane_b32 s13, v254, 25
	s_add_u32 s16, s13, s16
	v_readlane_b32 s13, v254, 26
	s_addc_u32 s17, s13, s17
	s_and_b64 s[18:19], s[2:3], exec
	s_cselect_b32 s15, s17, s29
	s_cselect_b32 s50, s16, s28
	s_ashr_i32 s13, s12, 31
	s_lshl_b64 s[18:19], s[12:13], 20
	s_add_u32 s18, s36, s18
	s_addc_u32 s19, s37, s19
	s_and_b64 s[34:35], s[2:3], exec
	s_cselect_b32 s13, s19, s31
	s_cselect_b32 s51, s18, s30
	s_add_u32 s28, s28, 0x80080
	s_addc_u32 s29, s29, 0
	s_add_u32 s52, s30, 0x100
	v_mov_b32_e32 v0, 0
	s_addc_u32 s53, s31, 0
	s_mov_b32 s54, -2
	v_mov_b32_e32 v1, v0
	v_mov_b64_e32 v[2:3], v[0:1]
	v_mov_b64_e32 v[4:5], v[0:1]
	v_mov_b64_e32 v[6:7], v[0:1]
	v_mov_b64_e32 v[8:9], v[0:1]
	v_mov_b64_e32 v[10:11], v[0:1]
	v_mov_b64_e32 v[12:13], v[0:1]
	v_mov_b64_e32 v[14:15], v[0:1]
	v_mov_b64_e32 v[16:17], v[0:1]
	v_mov_b64_e32 v[18:19], v[0:1]
	v_mov_b64_e32 v[20:21], v[0:1]
	v_mov_b64_e32 v[22:23], v[0:1]
	v_mov_b64_e32 v[24:25], v[0:1]
	v_mov_b64_e32 v[26:27], v[0:1]
	v_mov_b64_e32 v[28:29], v[0:1]
	v_mov_b64_e32 v[30:31], v[0:1]
	v_mov_b64_e32 v[32:33], v[0:1]
	v_mov_b64_e32 v[34:35], v[0:1]
	v_mov_b64_e32 v[36:37], v[0:1]
	v_mov_b64_e32 v[38:39], v[0:1]
	v_mov_b64_e32 v[40:41], v[0:1]
	v_mov_b64_e32 v[42:43], v[0:1]
	v_mov_b64_e32 v[44:45], v[0:1]
	v_mov_b64_e32 v[46:47], v[0:1]
	v_mov_b64_e32 v[48:49], v[0:1]
	v_mov_b64_e32 v[50:51], v[0:1]
	v_mov_b64_e32 v[52:53], v[0:1]
	v_mov_b64_e32 v[54:55], v[0:1]
	v_mov_b64_e32 v[56:57], v[0:1]
	v_mov_b64_e32 v[58:59], v[0:1]
	v_mov_b64_e32 v[60:61], v[0:1]
	v_mov_b64_e32 v[62:63], v[0:1]
	v_mov_b64_e32 v[64:65], v[0:1]
	v_mov_b64_e32 v[66:67], v[0:1]
	v_mov_b64_e32 v[68:69], v[0:1]
	v_mov_b64_e32 v[70:71], v[0:1]
	v_mov_b64_e32 v[72:73], v[0:1]
	v_mov_b64_e32 v[74:75], v[0:1]
	v_mov_b64_e32 v[76:77], v[0:1]
	v_mov_b64_e32 v[78:79], v[0:1]
	v_mov_b64_e32 v[80:81], v[0:1]
	v_mov_b64_e32 v[82:83], v[0:1]
	v_mov_b64_e32 v[84:85], v[0:1]
	v_mov_b64_e32 v[86:87], v[0:1]
	v_mov_b64_e32 v[88:89], v[0:1]
	v_mov_b64_e32 v[90:91], v[0:1]
	v_mov_b64_e32 v[92:93], v[0:1]
	v_mov_b64_e32 v[94:95], v[0:1]
	v_mov_b64_e32 v[96:97], v[0:1]
	v_mov_b64_e32 v[98:99], v[0:1]
	v_mov_b64_e32 v[100:101], v[0:1]
	v_mov_b64_e32 v[102:103], v[0:1]
	v_mov_b64_e32 v[104:105], v[0:1]
	v_mov_b64_e32 v[106:107], v[0:1]
	v_mov_b64_e32 v[108:109], v[0:1]
	v_mov_b64_e32 v[110:111], v[0:1]
	v_mov_b64_e32 v[112:113], v[0:1]
	v_mov_b64_e32 v[114:115], v[0:1]
	v_mov_b64_e32 v[116:117], v[0:1]
	v_mov_b64_e32 v[118:119], v[0:1]
	v_mov_b64_e32 v[120:121], v[0:1]
	v_mov_b64_e32 v[122:123], v[0:1]
	v_mov_b64_e32 v[124:125], v[0:1]
	v_mov_b64_e32 v[126:127], v[0:1]

.LBB0_1521:
	s_ashr_i32 s13, s12, 31
	s_lshl_b64 s[14:15], s[12:13], 22
	s_add_u32 s14, s34, s14
	s_addc_u32 s15, s35, s15
	s_and_b64 s[16:17], s[2:3], exec
	s_cselect_b32 s13, s15, s27
	s_cselect_b32 s48, s14, s26
	s_ashr_i32 s11, s10, 31
	s_lshl_b64 s[16:17], s[10:11], 22
	s_add_u32 s16, s36, s16
	s_addc_u32 s17, s37, s17
	s_and_b64 s[30:31], s[2:3], exec
	s_cselect_b32 s11, s17, s29
	s_cselect_b32 s49, s16, s28
	s_add_u32 s26, s26, 0x200080
	s_addc_u32 s27, s27, 0
	s_add_u32 s50, s28, 0x100
	v_mov_b32_e32 v0, 0
	s_addc_u32 s51, s29, 0
	s_mov_b32 s52, -2
	v_mov_b32_e32 v1, v0
	v_mov_b64_e32 v[2:3], v[0:1]
	v_mov_b64_e32 v[4:5], v[0:1]
	v_mov_b64_e32 v[6:7], v[0:1]
	v_mov_b64_e32 v[8:9], v[0:1]
	v_mov_b64_e32 v[10:11], v[0:1]
	v_mov_b64_e32 v[12:13], v[0:1]
	v_mov_b64_e32 v[14:15], v[0:1]
	v_mov_b64_e32 v[16:17], v[0:1]
	v_mov_b64_e32 v[18:19], v[0:1]
	v_mov_b64_e32 v[20:21], v[0:1]
	v_mov_b64_e32 v[22:23], v[0:1]
	v_mov_b64_e32 v[24:25], v[0:1]
	v_mov_b64_e32 v[26:27], v[0:1]
	v_mov_b64_e32 v[28:29], v[0:1]
	v_mov_b64_e32 v[30:31], v[0:1]
	v_mov_b64_e32 v[32:33], v[0:1]
	v_mov_b64_e32 v[34:35], v[0:1]
	v_mov_b64_e32 v[36:37], v[0:1]
	v_mov_b64_e32 v[38:39], v[0:1]
	v_mov_b64_e32 v[40:41], v[0:1]
	v_mov_b64_e32 v[42:43], v[0:1]
	v_mov_b64_e32 v[44:45], v[0:1]
	v_mov_b64_e32 v[46:47], v[0:1]
	v_mov_b64_e32 v[48:49], v[0:1]
	v_mov_b64_e32 v[50:51], v[0:1]
	v_mov_b64_e32 v[52:53], v[0:1]
	v_mov_b64_e32 v[54:55], v[0:1]
	v_mov_b64_e32 v[56:57], v[0:1]
	v_mov_b64_e32 v[58:59], v[0:1]
	v_mov_b64_e32 v[60:61], v[0:1]
	v_mov_b64_e32 v[62:63], v[0:1]
	v_mov_b64_e32 v[64:65], v[0:1]
	v_mov_b64_e32 v[66:67], v[0:1]
	v_mov_b64_e32 v[68:69], v[0:1]
	v_mov_b64_e32 v[70:71], v[0:1]
	v_mov_b64_e32 v[72:73], v[0:1]
	v_mov_b64_e32 v[74:75], v[0:1]
	v_mov_b64_e32 v[76:77], v[0:1]
	v_mov_b64_e32 v[78:79], v[0:1]
	v_mov_b64_e32 v[80:81], v[0:1]
	v_mov_b64_e32 v[82:83], v[0:1]
	v_mov_b64_e32 v[84:85], v[0:1]
	v_mov_b64_e32 v[86:87], v[0:1]
	v_mov_b64_e32 v[88:89], v[0:1]
	v_mov_b64_e32 v[90:91], v[0:1]
	v_mov_b64_e32 v[92:93], v[0:1]
	v_mov_b64_e32 v[94:95], v[0:1]
	v_mov_b64_e32 v[96:97], v[0:1]
	v_mov_b64_e32 v[98:99], v[0:1]
	v_mov_b64_e32 v[100:101], v[0:1]
	v_mov_b64_e32 v[102:103], v[0:1]
	v_mov_b64_e32 v[104:105], v[0:1]
	v_mov_b64_e32 v[106:107], v[0:1]
	v_mov_b64_e32 v[108:109], v[0:1]
	v_mov_b64_e32 v[110:111], v[0:1]
	v_mov_b64_e32 v[112:113], v[0:1]
	v_mov_b64_e32 v[114:115], v[0:1]
	v_mov_b64_e32 v[116:117], v[0:1]
	v_mov_b64_e32 v[118:119], v[0:1]
	v_mov_b64_e32 v[120:121], v[0:1]
	v_mov_b64_e32 v[122:123], v[0:1]
	v_mov_b64_e32 v[124:125], v[0:1]
	v_mov_b64_e32 v[126:127], v[0:1]
